# de-serialised loads in fox-gate and ssd-dt mini-GEMM tasks (all loads up front, unrolled reduce)
# speedup vs baseline: 1.0030x; 1.0030x over previous
.LBB0_717:
	s_lshl_b32 s26, s25, 6
	v_or_b32_e32 v2, s26, v179
	v_ashrrev_i32_e32 v3, 31, v2
	v_lshlrev_b64 v[22:23], 11, v[2:3]
	v_or_b32_e32 v42, 16, v2
	v_or_b32_e32 v54, 32, v2
	v_or_b32_e32 v2, 48, v2
	v_ashrrev_i32_e32 v43, 31, v42
	v_ashrrev_i32_e32 v55, 31, v54
	v_ashrrev_i32_e32 v3, 31, v2
	v_lshlrev_b64 v[66:67], 11, v[42:43]
	v_lshlrev_b64 v[68:69], 11, v[54:55]
	v_lshlrev_b64 v[2:3], 11, v[2:3]
	v_lshl_add_u64 v[76:77], v[10:11], 0, v[22:23]
	v_lshl_add_u64 v[78:79], v[10:11], 0, v[66:67]
	v_lshl_add_u64 v[80:81], v[10:11], 0, v[68:69]
	v_lshl_add_u64 v[82:83], v[10:11], 0, v[2:3]
	v_ashrrev_i32_e32 v85, 31, v29
	v_mov_b32_e32 v84, v29
	v_lshl_add_u64 v[84:85], v[84:85], 4, s[76:77]
	global_load_dword v86, v[12:13], off
	global_load_dword v87, v[14:15], off
	global_load_dwordx4 v[88:91], v[84:85], off
	global_load_dwordx4 v[92:95], v[84:85], off offset:512
	global_load_dwordx4 v[104:107], v[8:9], off
	global_load_dwordx4 v[120:123], v[76:77], off
	global_load_dwordx4 v[124:127], v[78:79], off
	global_load_dwordx4 v[128:131], v[80:81], off
	global_load_dwordx4 v[132:135], v[82:83], off
	global_load_dwordx4 v[108:111], v[8:9], off offset:64
	global_load_dwordx4 v[136:139], v[76:77], off offset:64
	global_load_dwordx4 v[140:143], v[78:79], off offset:64
	global_load_dwordx4 v[144:147], v[80:81], off offset:64
	global_load_dwordx4 v[148:151], v[82:83], off offset:64
	global_load_dwordx4 v[112:115], v[8:9], off offset:128
	global_load_dwordx4 v[152:155], v[76:77], off offset:128
	global_load_dwordx4 v[156:159], v[78:79], off offset:128
	global_load_dwordx4 v[160:163], v[80:81], off offset:128
	global_load_dwordx4 v[164:167], v[82:83], off offset:128
	global_load_dwordx4 v[116:119], v[8:9], off offset:192
	global_load_dwordx4 v[168:171], v[76:77], off offset:192
	global_load_dwordx4 v[172:175], v[78:79], off offset:192
	global_load_dwordx4 v[184:187], v[80:81], off offset:192
	global_load_dwordx4 v[180:183], v[82:83], off offset:192
	s_mov_b64 s[22:23], 0
	s_waitcnt vmcnt(18)
	v_mfma_f32_16x16x32_bf16 v[38:41], v[120:123], v[104:107], 0
	s_waitcnt vmcnt(17)
	v_mfma_f32_16x16x32_bf16 v[42:45], v[124:127], v[104:107], 0
	s_waitcnt vmcnt(16)
	v_mfma_f32_16x16x32_bf16 v[54:57], v[128:131], v[104:107], 0
	s_waitcnt vmcnt(15)
	v_mfma_f32_16x16x32_bf16 v[46:49], v[132:135], v[104:107], 0
	s_waitcnt vmcnt(13)
	v_mfma_f32_16x16x32_bf16 v[38:41], v[136:139], v[108:111], v[38:41]
	s_waitcnt vmcnt(12)
	v_mfma_f32_16x16x32_bf16 v[42:45], v[140:143], v[108:111], v[42:45]
	s_waitcnt vmcnt(11)
	v_mfma_f32_16x16x32_bf16 v[54:57], v[144:147], v[108:111], v[54:57]
	s_waitcnt vmcnt(10)
	v_mfma_f32_16x16x32_bf16 v[46:49], v[148:151], v[108:111], v[46:49]
	s_waitcnt vmcnt(8)
	v_mfma_f32_16x16x32_bf16 v[38:41], v[152:155], v[112:115], v[38:41]
	s_waitcnt vmcnt(7)
	v_mfma_f32_16x16x32_bf16 v[42:45], v[156:159], v[112:115], v[42:45]
	s_waitcnt vmcnt(6)
	v_mfma_f32_16x16x32_bf16 v[54:57], v[160:163], v[112:115], v[54:57]
	s_waitcnt vmcnt(5)
	v_mfma_f32_16x16x32_bf16 v[46:49], v[164:167], v[112:115], v[46:49]
	s_waitcnt vmcnt(3)
	v_mfma_f32_16x16x32_bf16 v[38:41], v[168:171], v[116:119], v[38:41]
	s_waitcnt vmcnt(2)
	v_mfma_f32_16x16x32_bf16 v[42:45], v[172:175], v[116:119], v[42:45]
	s_waitcnt vmcnt(1)
	v_mfma_f32_16x16x32_bf16 v[54:57], v[184:187], v[116:119], v[54:57]
	s_waitcnt vmcnt(0)
	v_mfma_f32_16x16x32_bf16 v[46:49], v[180:183], v[116:119], v[46:49]
	s_nop 7
	s_nop 3
	ds_write2_b32 v31, v38, v39 offset1:16
	ds_write2_b32 v31, v40, v41 offset0:32 offset1:48
	ds_write2_b32 v33, v42, v43 offset1:16
	ds_write2_b32 v33, v44, v45 offset0:32 offset1:48
	ds_write2_b32 v34, v54, v55 offset1:16
	ds_write2_b32 v34, v56, v57 offset0:32 offset1:48
	ds_write2_b32 v35, v46, v47 offset1:16
	ds_write2_b32 v35, v48, v49 offset0:32 offset1:48
	s_waitcnt vmcnt(0) lgkmcnt(0)
	s_barrier
.LBB0_718:
	ds_read2st64_b32 v[96:97], v30 offset1:16
	ds_read2st64_b32 v[98:99], v30 offset0:32 offset1:48
	ds_read2st64_b32 v[100:101], v30 offset0:64 offset1:80
	ds_read2st64_b32 v[102:103], v30 offset0:96 offset1:112
	ds_read2st64_b32 v[188:189], v30 offset0:8 offset1:24
	ds_read2st64_b32 v[190:191], v30 offset0:40 offset1:56
	ds_read2st64_b32 v[192:193], v30 offset0:72 offset1:88
	ds_read2st64_b32 v[194:195], v30 offset0:104 offset1:120
	v_add_f32_e32 v22, v89, v88
	v_add_f32_e32 v23, v90, v91
	v_add_f32_e32 v22, v22, v23
	v_fmamk_f32 v22, v22, 0x3a800000, v32
	v_rsq_f32_e32 v22, v22
	v_add_f32_e32 v42, v93, v92
	v_add_f32_e32 v23, v94, v95
	v_add_f32_e32 v42, v42, v23
	v_fmamk_f32 v42, v42, 0x3a800000, v32
	v_rsq_f32_e32 v42, v42
	s_waitcnt lgkmcnt(4)
	v_add_f32_e32 v3, 0, v96
	v_add_f32_e32 v3, v3, v97
	v_add_f32_e32 v3, v3, v98
	v_add_f32_e32 v3, v3, v99
	v_add_f32_e32 v3, v3, v100
	v_add_f32_e32 v3, v3, v101
	v_add_f32_e32 v3, v3, v102
	v_add_f32_e32 v3, v3, v103
	v_mul_f32_e32 v3, v3, v22
	ds_write_b32 v30, v3 offset:32768
	s_waitcnt lgkmcnt(1)
	v_add_f32_e32 v3, 0, v188
	v_add_f32_e32 v3, v3, v189
	v_add_f32_e32 v3, v3, v190
	v_add_f32_e32 v3, v3, v191
	v_add_f32_e32 v3, v3, v192
	v_add_f32_e32 v3, v3, v193
	v_add_f32_e32 v3, v3, v194
	v_add_f32_e32 v3, v3, v195
	v_mul_f32_e32 v3, v3, v42
	ds_write_b32 v30, v3 offset:34816
	s_or_b64 exec, exec, s[22:23]
	s_waitcnt vmcnt(0) lgkmcnt(0)
	s_barrier
	v_mov_b32_e32 v2, v86
	ds_read_b32 v3, v25 offset:32768
	v_and_b32_e32 v5, 64, v36
	v_add_u32_e32 v6, -1, v36
	v_cmp_lt_i32_e32 vcc, v6, v5
	s_ashr_i32 s23, s25, 3
	s_and_b32 s27, s23, -16
	v_cndmask_b32_e32 v6, v6, v36, vcc
	v_lshlrev_b32_e32 v38, 2, v6
	v_add_u32_e32 v6, -2, v36
	v_cmp_lt_i32_e32 vcc, v6, v5
	v_or_b32_e32 v22, s27, v24
	v_ashrrev_i32_e32 v23, 31, v22
	v_cndmask_b32_e32 v6, v6, v36, vcc
	v_lshlrev_b32_e32 v39, 2, v6
	v_add_u32_e32 v6, -4, v36
	v_cmp_lt_i32_e32 vcc, v6, v5
	s_and_b32 s22, s26, 0x1fc0
	s_bfe_u32 s26, s26, 0x70006
	v_cndmask_b32_e32 v6, v6, v36, vcc
	v_lshlrev_b32_e32 v40, 2, v6
	v_add_u32_e32 v6, -8, v36
	v_cmp_lt_i32_e32 vcc, v6, v5
	s_waitcnt vmcnt(0) lgkmcnt(0)
	v_add_f32_e32 v2, v3, v2
	v_mul_f32_e64 v3, |v2|, s1
	v_exp_f32_e32 v3, v3
	v_max_f32_e64 v2, -v2, 0
	v_cndmask_b32_e32 v6, v6, v36, vcc
	v_lshlrev_b32_e32 v41, 2, v6
	v_add_f32_e32 v3, 1.0, v3
	v_log_f32_e32 v3, v3
	v_add_u32_e32 v6, -16, v36
	v_cmp_lt_i32_e32 vcc, v6, v5
	v_fmac_f32_e32 v3, 0x3fb8aa3b, v2
	v_xor_b32_e32 v2, 0x80000000, v3
	ds_bpermute_b32 v2, v38, v2
	v_cndmask_b32_e32 v6, v6, v36, vcc
	v_lshlrev_b32_e32 v42, 2, v6
	v_subrev_u32_e32 v6, 32, v36
	v_cmp_lt_i32_e32 vcc, v6, v5
	s_waitcnt lgkmcnt(0)
	v_sub_f32_e32 v2, v2, v3
	v_cndmask_b32_e64 v2, v2, -v3, s[4:5]
	ds_bpermute_b32 v3, v39, v2
	v_cndmask_b32_e32 v5, v6, v36, vcc
	v_lshlrev_b32_e32 v43, 2, v5
	v_or_b32_e32 v6, s22, v1
	v_lshlrev_b32_e32 v6, 4, v6
	s_waitcnt lgkmcnt(0)
	v_add_f32_e32 v3, v2, v3
	v_cndmask_b32_e64 v2, v3, v2, s[6:7]
	ds_bpermute_b32 v3, v40, v2
	v_mov_b32_e32 v5, v7
	s_waitcnt lgkmcnt(0)
	v_add_f32_e32 v3, v2, v3
	v_cndmask_b32_e64 v2, v3, v2, s[8:9]
	ds_bpermute_b32 v3, v41, v2
	s_waitcnt lgkmcnt(0)
	v_add_f32_e32 v3, v2, v3
	v_cndmask_b32_e64 v2, v3, v2, s[10:11]
	ds_bpermute_b32 v3, v42, v2
	s_waitcnt lgkmcnt(0)
	v_add_f32_e32 v3, v2, v3
	v_cndmask_b32_e64 v2, v3, v2, s[12:13]
	ds_bpermute_b32 v3, v43, v2
	s_waitcnt lgkmcnt(0)
	v_add_f32_e32 v3, v2, v3
	v_cndmask_b32_e64 v45, v3, v2, s[14:15]
	ds_bpermute_b32 v44, v37, v45
	v_lshlrev_b64 v[2:3], 17, v[22:23]
	v_lshl_add_u64 v[46:47], s[2:3], 0, v[2:3]
	v_lshl_add_u64 v[46:47], v[46:47], 0, v[6:7]
	s_waitcnt lgkmcnt(0)
	v_sub_f32_e32 v2, v44, v45
	v_cvt_pk_bf16_f32 v3, v2, v2
	s_nop 0
	v_lshlrev_b32_e32 v23, 16, v3
	v_sub_f32_e32 v2, v2, v23
	v_cvt_pk_bf16_f32 v23, v2, v2
	s_nop 0
	v_lshlrev_b32_e32 v23, 16, v23
	v_sub_f32_e32 v45, v2, v23
	v_and_or_b32 v2, v3, s24, v23
	v_cvt_pk_bf16_f32 v3, v45, v45
	s_nop 0
	v_and_or_b32 v3, v3, s24, 1.0
	global_store_dwordx4 v[46:47], v[2:5], off
	s_and_saveexec_b64 s[22:23], s[4:5]
	s_cbranch_execz .LBB0_721
	v_exp_f32_e32 v5, v44
	v_lshl_or_b32 v2, v22, 7, s26
	v_ashrrev_i32_e32 v3, 31, v2
	v_lshlrev_b64 v[2:3], 2, v[2:3]
	v_lshl_add_u64 v[22:23], s[18:19], 0, v[2:3]
	v_lshl_add_u64 v[2:3], s[20:21], 0, v[2:3]
	global_store_dword v[22:23], v5, off
	global_store_dword v[2:3], v44, off
.LBB0_721:
	s_or_b64 exec, exec, s[22:23]
	v_mov_b32_e32 v2, v87
	ds_read_b32 v3, v27 offset:32768
	v_add_u32_e32 v22, s27, v26
	v_ashrrev_i32_e32 v23, 31, v22
	v_mov_b32_e32 v5, v7
	s_waitcnt lgkmcnt(0)
	v_add_f32_e32 v2, v3, v2
	v_mul_f32_e64 v3, |v2|, s1
	v_exp_f32_e32 v3, v3
	v_max_f32_e64 v2, -v2, 0
	v_add_f32_e32 v3, 1.0, v3
	v_log_f32_e32 v3, v3
	s_nop 0
	v_fmac_f32_e32 v3, 0x3fb8aa3b, v2
	v_xor_b32_e32 v2, 0x80000000, v3
	ds_bpermute_b32 v2, v38, v2
	s_waitcnt lgkmcnt(0)
	v_sub_f32_e32 v2, v2, v3
	v_cndmask_b32_e64 v2, v2, -v3, s[4:5]
	ds_bpermute_b32 v3, v39, v2
	s_waitcnt lgkmcnt(0)
	v_add_f32_e32 v3, v2, v3
	v_cndmask_b32_e64 v2, v3, v2, s[6:7]
	ds_bpermute_b32 v3, v40, v2
	s_waitcnt lgkmcnt(0)
	v_add_f32_e32 v3, v2, v3
	v_cndmask_b32_e64 v2, v3, v2, s[8:9]
	ds_bpermute_b32 v3, v41, v2
	s_waitcnt lgkmcnt(0)
	v_add_f32_e32 v3, v2, v3
	v_cndmask_b32_e64 v2, v3, v2, s[10:11]
	ds_bpermute_b32 v3, v42, v2
	s_waitcnt lgkmcnt(0)
	v_add_f32_e32 v3, v2, v3
	v_cndmask_b32_e64 v2, v3, v2, s[12:13]
	ds_bpermute_b32 v3, v43, v2
	s_waitcnt lgkmcnt(0)
	v_add_f32_e32 v3, v2, v3
	v_cndmask_b32_e64 v39, v3, v2, s[14:15]
	ds_bpermute_b32 v38, v37, v39
	v_lshlrev_b64 v[2:3], 17, v[22:23]
	v_lshl_add_u64 v[40:41], s[2:3], 0, v[2:3]
	v_lshl_add_u64 v[40:41], v[40:41], 0, v[6:7]
	s_waitcnt lgkmcnt(0)
	v_sub_f32_e32 v2, v38, v39
	v_cvt_pk_bf16_f32 v3, v2, v2
	s_nop 0
	v_lshlrev_b32_e32 v23, 16, v3
	v_sub_f32_e32 v2, v2, v23
	v_cvt_pk_bf16_f32 v23, v2, v2
	s_nop 0
	v_lshlrev_b32_e32 v23, 16, v23
	v_sub_f32_e32 v39, v2, v23
	v_and_or_b32 v2, v3, s24, v23
	v_cvt_pk_bf16_f32 v3, v39, v39
	s_nop 0
	v_and_or_b32 v3, v3, s24, 1.0
	global_store_dwordx4 v[40:41], v[2:5], off
	s_and_saveexec_b64 s[22:23], s[4:5]
	s_cbranch_execz .LBB0_716
	v_exp_f32_e32 v5, v38
	v_lshl_or_b32 v2, v22, 7, s26
	v_ashrrev_i32_e32 v3, 31, v2
	v_lshlrev_b64 v[2:3], 2, v[2:3]
	v_lshl_add_u64 v[22:23], s[18:19], 0, v[2:3]
	v_lshl_add_u64 v[2:3], s[20:21], 0, v[2:3]
	global_store_dword v[22:23], v5, off
	global_store_dword v[2:3], v38, off
	s_branch .LBB0_716

.LBB0_1296:
	s_lshl_b32 s21, s20, 6
	v_or_b32_e32 v72, s21, v159
	v_or_b32_e32 v60, 16, v72
	v_or_b32_e32 v68, 32, v72
	v_or_b32_e32 v76, 48, v72
	v_ashrrev_i32_e32 v73, 31, v72
	v_ashrrev_i32_e32 v61, 31, v60
	v_ashrrev_i32_e32 v69, 31, v68
	v_ashrrev_i32_e32 v77, 31, v76
	v_lshlrev_b64 v[84:85], 11, v[72:73]
	v_lshlrev_b64 v[96:97], 11, v[60:61]
	v_lshlrev_b64 v[98:99], 11, v[68:69]
	v_lshlrev_b64 v[100:101], 11, v[76:77]
	v_lshl_add_u64 v[210:211], v[12:13], 0, v[84:85]
	v_lshl_add_u64 v[212:213], v[12:13], 0, v[96:97]
	v_lshl_add_u64 v[214:215], v[12:13], 0, v[98:99]
	v_lshl_add_u64 v[216:217], v[12:13], 0, v[100:101]
	v_mov_b32_e32 v218, v48
	v_ashrrev_i32_e32 v219, 31, v48
	v_lshl_add_u64 v[218:219], v[218:219], 4, s[76:77]
	global_load_dwordx3 v[236:238], v[26:27], off
	global_load_dwordx3 v[240:242], v[28:29], off
	global_load_dword v244, v[30:31], off
	global_load_dword v245, v[32:33], off
	global_load_dwordx4 v[220:223], v[218:219], off
	global_load_dwordx4 v[224:227], v[218:219], off offset:256
	global_load_dwordx4 v[228:231], v[218:219], off offset:512
	global_load_dwordx4 v[232:235], v[218:219], off offset:768
	global_load_dwordx4 v[176:179], v[8:9], off
	global_load_dwordx4 v[180:183], v[10:11], off
	global_load_dwordx4 v[110:113], v[210:211], off
	global_load_dwordx4 v[114:117], v[212:213], off
	global_load_dwordx4 v[118:121], v[214:215], off
	global_load_dwordx4 v[122:125], v[216:217], off
	global_load_dwordx4 v[184:187], v[8:9], off offset:64
	global_load_dwordx4 v[188:191], v[10:11], off offset:64
	global_load_dwordx4 v[126:129], v[210:211], off offset:64
	global_load_dwordx4 v[130:133], v[212:213], off offset:64
	global_load_dwordx4 v[134:137], v[214:215], off offset:64
	global_load_dwordx4 v[138:141], v[216:217], off offset:64
	global_load_dwordx4 v[192:195], v[8:9], off offset:128
	global_load_dwordx4 v[196:199], v[10:11], off offset:128
	global_load_dwordx4 v[142:145], v[210:211], off offset:128
	global_load_dwordx4 v[146:149], v[212:213], off offset:128
	global_load_dwordx4 v[150:153], v[214:215], off offset:128
	global_load_dwordx4 v[154:157], v[216:217], off offset:128
	global_load_dwordx4 v[200:203], v[8:9], off offset:192
	global_load_dwordx4 v[206:209], v[10:11], off offset:192
	global_load_dwordx4 v[160:163], v[210:211], off offset:192
	global_load_dwordx4 v[164:167], v[212:213], off offset:192
	global_load_dwordx4 v[168:171], v[214:215], off offset:192
	global_load_dwordx4 v[172:175], v[216:217], off offset:192
	s_mov_b64 s[22:23], 0
	v_add_u32_e32 v84, 0x800, v49
	v_add_u32_e32 v85, 0x1000, v49
	v_add_u32_e32 v86, 0x1800, v49
	s_waitcnt vmcnt(21)
	v_mfma_f32_16x16x32_bf16 v[52:55], v[110:113], v[176:179], 0
	v_mfma_f32_16x16x32_bf16 v[56:59], v[110:113], v[180:183], 0
	s_waitcnt vmcnt(20)
	v_mfma_f32_16x16x32_bf16 v[60:63], v[114:117], v[176:179], 0
	v_mfma_f32_16x16x32_bf16 v[64:67], v[114:117], v[180:183], 0
	s_waitcnt vmcnt(19)
	v_mfma_f32_16x16x32_bf16 v[68:71], v[118:121], v[176:179], 0
	v_mfma_f32_16x16x32_bf16 v[72:75], v[118:121], v[180:183], 0
	s_waitcnt vmcnt(18)
	v_mfma_f32_16x16x32_bf16 v[76:79], v[122:125], v[176:179], 0
	v_mfma_f32_16x16x32_bf16 v[80:83], v[122:125], v[180:183], 0
	s_waitcnt vmcnt(15)
	v_mfma_f32_16x16x32_bf16 v[52:55], v[126:129], v[184:187], v[52:55]
	v_mfma_f32_16x16x32_bf16 v[56:59], v[126:129], v[188:191], v[56:59]
	s_waitcnt vmcnt(14)
	v_mfma_f32_16x16x32_bf16 v[60:63], v[130:133], v[184:187], v[60:63]
	v_mfma_f32_16x16x32_bf16 v[64:67], v[130:133], v[188:191], v[64:67]
	s_waitcnt vmcnt(13)
	v_mfma_f32_16x16x32_bf16 v[68:71], v[134:137], v[184:187], v[68:71]
	v_mfma_f32_16x16x32_bf16 v[72:75], v[134:137], v[188:191], v[72:75]
	s_waitcnt vmcnt(12)
	v_mfma_f32_16x16x32_bf16 v[76:79], v[138:141], v[184:187], v[76:79]
	v_mfma_f32_16x16x32_bf16 v[80:83], v[138:141], v[188:191], v[80:83]
	s_waitcnt vmcnt(9)
	v_mfma_f32_16x16x32_bf16 v[52:55], v[142:145], v[192:195], v[52:55]
	v_mfma_f32_16x16x32_bf16 v[56:59], v[142:145], v[196:199], v[56:59]
	s_waitcnt vmcnt(8)
	v_mfma_f32_16x16x32_bf16 v[60:63], v[146:149], v[192:195], v[60:63]
	v_mfma_f32_16x16x32_bf16 v[64:67], v[146:149], v[196:199], v[64:67]
	s_waitcnt vmcnt(7)
	v_mfma_f32_16x16x32_bf16 v[68:71], v[150:153], v[192:195], v[68:71]
	v_mfma_f32_16x16x32_bf16 v[72:75], v[150:153], v[196:199], v[72:75]
	s_waitcnt vmcnt(6)
	v_mfma_f32_16x16x32_bf16 v[76:79], v[154:157], v[192:195], v[76:79]
	v_mfma_f32_16x16x32_bf16 v[80:83], v[154:157], v[196:199], v[80:83]
	s_waitcnt vmcnt(3)
	v_mfma_f32_16x16x32_bf16 v[52:55], v[160:163], v[200:203], v[52:55]
	v_mfma_f32_16x16x32_bf16 v[56:59], v[160:163], v[206:209], v[56:59]
	s_waitcnt vmcnt(2)
	v_mfma_f32_16x16x32_bf16 v[60:63], v[164:167], v[200:203], v[60:63]
	v_mfma_f32_16x16x32_bf16 v[64:67], v[164:167], v[206:209], v[64:67]
	s_waitcnt vmcnt(1)
	v_mfma_f32_16x16x32_bf16 v[68:71], v[168:171], v[200:203], v[68:71]
	v_mfma_f32_16x16x32_bf16 v[72:75], v[168:171], v[206:209], v[72:75]
	s_waitcnt vmcnt(0)
	v_mfma_f32_16x16x32_bf16 v[76:79], v[172:175], v[200:203], v[76:79]
	v_mfma_f32_16x16x32_bf16 v[80:83], v[172:175], v[206:209], v[80:83]
	s_nop 7
	s_nop 3
	ds_write2_b32 v49, v52, v56 offset1:16
	ds_write2_b32 v49, v53, v57 offset0:32 offset1:48
	ds_write2_b32 v49, v54, v58 offset0:64 offset1:80
	ds_write2_b32 v49, v55, v59 offset0:96 offset1:112
	ds_write2_b32 v84, v60, v64 offset1:16
	ds_write2_b32 v84, v61, v65 offset0:32 offset1:48
	ds_write2_b32 v84, v62, v66 offset0:64 offset1:80
	ds_write2_b32 v84, v63, v67 offset0:96 offset1:112
	ds_write2_b32 v85, v68, v72 offset1:16
	ds_write2_b32 v85, v69, v73 offset0:32 offset1:48
	ds_write2_b32 v85, v70, v74 offset0:64 offset1:80
	ds_write2_b32 v85, v71, v75 offset0:96 offset1:112
	ds_write2_b32 v86, v76, v80 offset1:16
	ds_write2_b32 v86, v77, v81 offset0:32 offset1:48
	ds_write2_b32 v86, v78, v82 offset0:64 offset1:80
	ds_write2_b32 v86, v79, v83 offset0:96 offset1:112
	s_waitcnt vmcnt(0) lgkmcnt(0)
	s_barrier
	v_mov_b32_e32 v2, v48
	v_mov_b32_e32 v4, v47
	v_mov_b32_e32 v5, v46
.LBB0_1297:
	ds_read2st64_b32 v[110:111], v47 offset1:32
	ds_read2st64_b32 v[112:113], v47 offset0:64 offset1:96
	ds_read2st64_b32 v[114:115], v47 offset0:128 offset1:160
	ds_read2st64_b32 v[116:117], v47 offset0:192 offset1:224
	ds_read2st64_b32 v[118:119], v47 offset0:8 offset1:40
	ds_read2st64_b32 v[120:121], v47 offset0:72 offset1:104
	ds_read2st64_b32 v[122:123], v47 offset0:136 offset1:168
	ds_read2st64_b32 v[124:125], v47 offset0:200 offset1:232
	ds_read2st64_b32 v[126:127], v47 offset0:16 offset1:48
	ds_read2st64_b32 v[128:129], v47 offset0:80 offset1:112
	ds_read2st64_b32 v[130:131], v47 offset0:144 offset1:176
	ds_read2st64_b32 v[132:133], v47 offset0:208 offset1:240
	ds_read2st64_b32 v[134:135], v47 offset0:24 offset1:56
	ds_read2st64_b32 v[136:137], v47 offset0:88 offset1:120
	ds_read2st64_b32 v[138:139], v47 offset0:152 offset1:184
	ds_read2st64_b32 v[140:141], v47 offset0:216 offset1:248
	v_add_u32_e32 v142, 0x10000, v47
	v_add_f32_e32 v143, v221, v220
	v_add_f32_e32 v147, v222, v223
	v_add_f32_e32 v143, v143, v147
	v_fmamk_f32 v143, v143, 0x3a800000, v50
	v_rsq_f32_e32 v143, v143
	v_add_f32_e32 v144, v225, v224
	v_add_f32_e32 v147, v226, v227
	v_add_f32_e32 v144, v144, v147
	v_fmamk_f32 v144, v144, 0x3a800000, v50
	v_rsq_f32_e32 v144, v144
	v_add_f32_e32 v145, v229, v228
	v_add_f32_e32 v147, v230, v231
	v_add_f32_e32 v145, v145, v147
	v_fmamk_f32 v145, v145, 0x3a800000, v50
	v_rsq_f32_e32 v145, v145
	v_add_f32_e32 v146, v233, v232
	v_add_f32_e32 v147, v234, v235
	v_add_f32_e32 v146, v146, v147
	v_fmamk_f32 v146, v146, 0x3a800000, v50
	v_rsq_f32_e32 v146, v146
	s_waitcnt lgkmcnt(12)
	v_add_f32_e32 v148, 0, v110
	v_add_f32_e32 v148, v148, v111
	v_add_f32_e32 v148, v148, v112
	v_add_f32_e32 v148, v148, v113
	v_add_f32_e32 v148, v148, v114
	v_add_f32_e32 v148, v148, v115
	v_add_f32_e32 v148, v148, v116
	v_add_f32_e32 v148, v148, v117
	v_mul_f32_e32 v148, v148, v143
	ds_write_b32 v142, v148
	s_waitcnt lgkmcnt(8)
	v_add_f32_e32 v148, 0, v118
	v_add_f32_e32 v148, v148, v119
	v_add_f32_e32 v148, v148, v120
	v_add_f32_e32 v148, v148, v121
	v_add_f32_e32 v148, v148, v122
	v_add_f32_e32 v148, v148, v123
	v_add_f32_e32 v148, v148, v124
	v_add_f32_e32 v148, v148, v125
	v_mul_f32_e32 v148, v148, v144
	ds_write_b32 v142, v148 offset:2048
	s_waitcnt lgkmcnt(4)
	v_add_f32_e32 v148, 0, v126
	v_add_f32_e32 v148, v148, v127
	v_add_f32_e32 v148, v148, v128
	v_add_f32_e32 v148, v148, v129
	v_add_f32_e32 v148, v148, v130
	v_add_f32_e32 v148, v148, v131
	v_add_f32_e32 v148, v148, v132
	v_add_f32_e32 v148, v148, v133
	v_mul_f32_e32 v148, v148, v145
	ds_write_b32 v142, v148 offset:4096
	s_waitcnt lgkmcnt(0)
	v_add_f32_e32 v148, 0, v134
	v_add_f32_e32 v148, v148, v135
	v_add_f32_e32 v148, v148, v136
	v_add_f32_e32 v148, v148, v137
	v_add_f32_e32 v148, v148, v138
	v_add_f32_e32 v148, v148, v139
	v_add_f32_e32 v148, v148, v140
	v_add_f32_e32 v148, v148, v141
	v_mul_f32_e32 v148, v148, v146
	ds_write_b32 v142, v148 offset:6144
	s_or_b64 exec, exec, s[22:23]
	s_waitcnt vmcnt(0) lgkmcnt(0)
	s_barrier
	v_mov_b32_e32 v2, v236
	v_mov_b32_e32 v3, v237
	v_mov_b32_e32 v4, v238
	v_mov_b32_e32 v52, v240
	v_mov_b32_e32 v53, v241
	v_mov_b32_e32 v54, v242
	v_mov_b32_e32 v5, v244
	v_mov_b32_e32 v41, v245
	v_and_b32_e32 v43, 64, v51
	v_add_u32_e32 v55, -1, v51
	v_add_u32_e32 v59, -2, v51
	v_cmp_lt_i32_e64 s[16:17], v55, v43
	v_add_u32_e32 v60, -4, v51
	v_add_u32_e32 v61, -8, v51
	v_cndmask_b32_e64 v55, v55, v51, s[16:17]
	v_cmp_lt_i32_e64 s[16:17], v59, v43
	v_add_u32_e32 v62, -16, v51
	v_subrev_u32_e32 v63, 32, v51
	v_cndmask_b32_e64 v59, v59, v51, s[16:17]
	v_cmp_lt_i32_e64 s[16:17], v60, v43
	ds_read_b96 v[56:58], v44
	v_lshlrev_b32_e32 v64, 2, v55
	v_cndmask_b32_e64 v60, v60, v51, s[16:17]
	v_cmp_lt_i32_e64 s[16:17], v61, v43
	v_lshlrev_b32_e32 v59, 2, v59
	v_lshlrev_b32_e32 v60, 2, v60
	v_cndmask_b32_e64 v61, v61, v51, s[16:17]
	v_cmp_lt_i32_e64 s[16:17], v62, v43
	s_waitcnt vmcnt(2)
	v_mul_f32_e32 v52, 0x3fb8aa3b, v52
	v_cndmask_b32_e64 v62, v62, v51, s[16:17]
	v_cmp_lt_i32_e64 s[16:17], v63, v43
	v_mul_f32_e32 v53, 0x3fb8aa3b, v53
	v_mul_f32_e32 v54, 0x3fb8aa3b, v54
	v_cndmask_b32_e64 v43, v63, v51, s[16:17]
	ds_read_b32 v63, v45
	s_waitcnt lgkmcnt(1)
	v_add_f32_e32 v55, v56, v2
	v_add_f32_e32 v56, v57, v3
	v_add_f32_e32 v57, v58, v4
	v_max_f32_e32 v2, 0, v55
	s_waitcnt vmcnt(1) lgkmcnt(0)
	v_add_f32_e32 v5, v63, v5
	v_mul_f32_e64 v55, |v55|, s3
	v_exp_f32_e32 v58, v52
	v_mul_f32_e64 v52, |v56|, s3
	v_max_f32_e32 v3, 0, v56
	v_exp_f32_e32 v56, v53
	v_max_f32_e32 v4, 0, v57
	v_mul_f32_e64 v53, |v57|, s3
	v_exp_f32_e32 v57, v54
	v_mul_f32_e64 v54, |v5|, s3
	v_exp_f32_e32 v55, v55
	v_exp_f32_e32 v52, v52
	v_exp_f32_e32 v53, v53
	v_exp_f32_e32 v54, v54
	v_add_f32_e32 v55, 1.0, v55
	v_add_f32_e32 v63, 1.0, v52
	v_add_f32_e32 v65, 1.0, v53
	v_add_f32_e32 v66, 1.0, v54
	v_log_f32_e32 v52, v55
	v_log_f32_e32 v53, v63
	s_waitcnt vmcnt(0)
	v_mul_f32_e32 v41, 0x3fb8aa3b, v41
	v_log_f32_e32 v54, v65
	v_log_f32_e32 v55, v66
	v_exp_f32_e32 v41, v41
	v_max_f32_e32 v5, 0, v5
	v_pk_fma_f32 v[52:53], v[52:53], s[2:3], v[2:3] op_sel_hi:[1,0,1]
	v_pk_fma_f32 v[54:55], v[54:55], s[2:3], v[4:5] op_sel_hi:[1,0,1]
	v_mul_f32_e64 v2, v52, -v58
	v_mul_f32_e64 v5, v55, -v41
	v_mul_f32_e32 v41, 0x3fb8aa3b, v2
	ds_bpermute_b32 v63, v64, v41
	v_mul_f32_e64 v3, v53, -v56
	v_mul_f32_e32 v56, 0x3fb8aa3b, v3
	ds_bpermute_b32 v65, v64, v56
	v_mul_f32_e64 v4, v54, -v57
	v_mul_f32_e32 v57, 0x3fb8aa3b, v4
	s_waitcnt lgkmcnt(1)
	v_fmac_f32_e32 v63, 0x3fb8aa3b, v2
	v_mul_f32_e32 v58, 0x3fb8aa3b, v5
	ds_bpermute_b32 v66, v64, v57
	v_cndmask_b32_e32 v2, v63, v41, vcc
	ds_bpermute_b32 v64, v64, v58
	ds_bpermute_b32 v41, v59, v2
	s_waitcnt lgkmcnt(3)
	v_fmac_f32_e32 v65, 0x3fb8aa3b, v3
	v_cndmask_b32_e32 v3, v65, v56, vcc
	ds_bpermute_b32 v56, v59, v3
	s_waitcnt lgkmcnt(3)
	v_fmac_f32_e32 v66, 0x3fb8aa3b, v4
	s_waitcnt lgkmcnt(2)
	v_fmac_f32_e32 v64, 0x3fb8aa3b, v5
	v_cndmask_b32_e32 v4, v66, v57, vcc
	s_waitcnt lgkmcnt(1)
	v_add_f32_e32 v41, v2, v41
	v_cndmask_b32_e32 v5, v64, v58, vcc
	ds_bpermute_b32 v57, v59, v4
	v_cndmask_b32_e64 v2, v41, v2, s[4:5]
	ds_bpermute_b32 v58, v59, v5
	ds_bpermute_b32 v41, v60, v2
	s_waitcnt lgkmcnt(3)
	v_add_f32_e32 v56, v3, v56
	v_cndmask_b32_e64 v3, v56, v3, s[4:5]
	ds_bpermute_b32 v56, v60, v3
	s_waitcnt lgkmcnt(3)
	v_add_f32_e32 v57, v4, v57
	s_waitcnt lgkmcnt(2)
	v_add_f32_e32 v58, v5, v58
	v_cndmask_b32_e64 v4, v57, v4, s[4:5]
	s_waitcnt lgkmcnt(1)
	v_add_f32_e32 v41, v2, v41
	v_lshlrev_b32_e32 v59, 2, v61
	v_cndmask_b32_e64 v5, v58, v5, s[4:5]
	ds_bpermute_b32 v57, v60, v4
	v_cndmask_b32_e64 v2, v41, v2, s[6:7]
	ds_bpermute_b32 v58, v60, v5
	ds_bpermute_b32 v41, v59, v2
	s_waitcnt lgkmcnt(3)
	v_add_f32_e32 v56, v3, v56
	v_cndmask_b32_e64 v3, v56, v3, s[6:7]
	ds_bpermute_b32 v56, v59, v3
	s_waitcnt lgkmcnt(3)
	v_add_f32_e32 v57, v4, v57
	s_waitcnt lgkmcnt(2)
	v_add_f32_e32 v58, v5, v58
	v_cndmask_b32_e64 v4, v57, v4, s[6:7]
	s_waitcnt lgkmcnt(1)
	v_add_f32_e32 v41, v2, v41
	v_lshlrev_b32_e32 v60, 2, v62
	v_cndmask_b32_e64 v5, v58, v5, s[6:7]
	ds_bpermute_b32 v57, v59, v4
	v_cndmask_b32_e64 v2, v41, v2, s[8:9]
	ds_bpermute_b32 v58, v59, v5
	ds_bpermute_b32 v41, v60, v2
	s_waitcnt lgkmcnt(3)
	v_add_f32_e32 v56, v3, v56
	v_cndmask_b32_e64 v3, v56, v3, s[8:9]
	ds_bpermute_b32 v56, v60, v3
	s_waitcnt lgkmcnt(3)
	v_add_f32_e32 v57, v4, v57
	s_waitcnt lgkmcnt(2)
	v_add_f32_e32 v58, v5, v58
	v_cndmask_b32_e64 v4, v57, v4, s[8:9]
	s_waitcnt lgkmcnt(1)
	v_add_f32_e32 v41, v2, v41
	v_lshlrev_b32_e32 v43, 2, v43
	v_cndmask_b32_e64 v5, v58, v5, s[8:9]
	ds_bpermute_b32 v57, v60, v4
	v_cndmask_b32_e64 v2, v41, v2, s[10:11]
	ds_bpermute_b32 v58, v60, v5
	ds_bpermute_b32 v41, v43, v2
	s_waitcnt lgkmcnt(3)
	v_add_f32_e32 v56, v3, v56
	v_cndmask_b32_e64 v3, v56, v3, s[10:11]
	ds_bpermute_b32 v56, v43, v3
	s_waitcnt lgkmcnt(3)
	v_add_f32_e32 v57, v4, v57
	s_waitcnt lgkmcnt(1)
	v_add_f32_e32 v41, v2, v41
	v_cndmask_b32_e64 v4, v57, v4, s[10:11]
	v_add_f32_e32 v57, v5, v58
	v_cndmask_b32_e64 v2, v41, v2, s[12:13]
	ds_bpermute_b32 v41, v43, v4
	v_cndmask_b32_e64 v5, v57, v5, s[10:11]
	ds_bpermute_b32 v43, v43, v5
	s_waitcnt lgkmcnt(2)
	v_add_f32_e32 v56, v3, v56
	v_cndmask_b32_e64 v3, v56, v3, s[12:13]
	v_or_b32_e32 v56, s21, v1
	v_ashrrev_i32_e32 v57, 31, v56
	s_waitcnt lgkmcnt(1)
	v_add_f32_e32 v41, v4, v41
	v_lshlrev_b64 v[56:57], 7, v[56:57]
	v_cndmask_b32_e64 v4, v41, v4, s[12:13]
	s_waitcnt lgkmcnt(0)
	v_add_f32_e32 v41, v5, v43
	v_lshl_add_u64 v[58:59], v[34:35], 0, v[56:57]
	v_cndmask_b32_e64 v5, v41, v5, s[12:13]
	global_store_dwordx4 v[58:59], v[52:55], off
	s_nop 1
	v_lshl_add_u64 v[52:53], v[36:37], 0, v[56:57]
	global_store_dwordx4 v[52:53], v[2:5], off
	s_and_saveexec_b64 s[16:17], s[14:15]
	s_cbranch_execz .LBB0_1295
	s_ashr_i32 s21, s20, 31
	s_lshl_b64 s[22:23], s[20:21], 7
	v_lshl_add_u64 v[52:53], v[38:39], 0, s[22:23]
	global_store_dwordx4 v[52:53], v[2:5], off
	s_branch .LBB0_1295
